# attention first key tile: the 12 serialized QK LDS reads issued up front into 12 buffers (counted lgkmcnt), on top of the zero-P chunk removal
# speedup vs baseline: 1.0040x; 1.0015x over previous
; #define LAS __attribute__((address_space(3)))
; __device__ __forceinline__ int pi32(int r) { return (r & 0x13) | ((r & 4) << 1) | ((r & 8) >> 1); }
; __device__ __forceinline__ void attn_unit(LAS unsigned char* lds, const bf16_t* Q, const bf16_t* KN, const bf16_t* KPE, const bf16_t* VT, bf16_t* Y, float* ssq_b, int b, int h, int qg) {
;     const int tid = threadIdx.x, wid = __builtin_amdgcn_readfirstlane(tid >> 6), lane = tid & 63, q = lane & 31, hh = lane >> 5;
;     const int t0 = 16 + 256 * qg, c0 = 1 + 4 * qg, cw = c0 + (wid >> 1), ntiles = c0 + 4;
;     bf16x8 qf[12];
;     {
;         const bf16_t* qp = Q + (size_t)(b * 2048 + (t0 - 16) + 32 * wid + q) * 1536 + h * 192 + 8 * hh;
; #pragma unroll
;         for (int ks = 0; ks < 12; ++ks) qf[ks] = *(const bf16x8*)(qp + 16 * ks);
;     }
;     f32x16 o[4];
; #pragma unroll
;     for (int d = 0; d < 4; ++d)
; #pragma unroll
;         for (int i = 0; i < 16; ++i) o[d][i] = 0.f;
;     float mrun = -INFINITY, lsum = 0.f;
;     const char* ksrc[3]; unsigned kstr[3]; const char* vsrc[2];
; #pragma unroll
;     for (int i = 0; i < 3; ++i) {
;         const int s = 64 * (wid * 3 + i) + lane; const int key = s / 24, pos = s - key * 24; const int pc = pos ^ ((key >> 1) & 7);
;         const size_t row = (size_t)b * 2048 + key;
;         if (pc < 16) { ksrc[i] = (const char*)(KN + row * 1024 + h * 128 + pc * 8); kstr[i] = 2048u; }
;         else { ksrc[i] = (const char*)(KPE + row * 64 + (pc - 16) * 8); kstr[i] = 128u; }
;     }
; #pragma unroll
;     for (int i = 0; i < 2; ++i) {
;         const int s = 64 * (wid * 2 + i) + lane; const int d = s >> 3, pos = s & 7; const int pc = pos ^ ((d >> 1) & 7);
;         vsrc[i] = (const char*)(VT + ((size_t)((b * 8 + h) * 128 + d)) * 2048 + pc * 8);
;     }
;     ...
;     const int key0 = pi32(q);
;     const unsigned kbase0 = (unsigned)(key0 * 384) + (unsigned)(((hh ^ ((key0 >> 1) & 7))) << 4);
;     const unsigned vbase0 = (unsigned)(q * 128) + (unsigned)((hh ^ ((q >> 1) & 7)) << 4);
;     AT_DMA(0); __syncthreads();
.LBB0_652:
	s_lshl_b32 s6, s39, 3
	s_and_b32 s6, s6, 56
	s_ashr_i32 s7, s39, 5
	s_add_i32 s6, s6, s7
	s_bfe_u32 s45, s39, 0x20003
	s_ashr_i32 s8, s6, 3
	s_xor_b32 s52, s45, 7
	v_readfirstlane_b32 s53, v170
	s_lshl_b32 s13, s8, 11
	s_lshr_b32 s56, s53, 6
	s_lshl_b32 s28, s52, 8
	v_or_b32_e32 v211, s13, v149
	s_lshl_b32 s12, s56, 5
	v_or_b32_e32 v0, s28, v211
	v_add_u32_e32 v2, s12, v0
	s_waitcnt lgkmcnt(0)
	v_mov_b64_e32 v[0:1], s[60:61]
	s_and_b32 s29, s7, 7
	v_mad_i64_i32 v[0:1], s[6:7], v2, s31, v[0:1]
	s_mul_i32 s6, s29, 0xc0
	s_lshl_b32 s16, s6, 1
	v_lshl_add_u64 v[0:1], v[0:1], 0, s[16:17]
	v_mov_b32_e32 v157, v151
	v_lshl_add_u64 v[0:1], v[0:1], 0, v[156:157]
	global_load_dwordx4 v[140:143], v[0:1], off
	global_load_dwordx4 v[136:139], v[0:1], off offset:32
	global_load_dwordx4 v[132:135], v[0:1], off offset:64
	global_load_dwordx4 v[128:131], v[0:1], off offset:96
	global_load_dwordx4 v[124:127], v[0:1], off offset:128
	global_load_dwordx4 v[120:123], v[0:1], off offset:160
	global_load_dwordx4 v[116:119], v[0:1], off offset:192
	global_load_dwordx4 v[112:115], v[0:1], off offset:224
	global_load_dwordx4 v[108:111], v[0:1], off offset:256
	global_load_dwordx4 v[104:107], v[0:1], off offset:288
	global_load_dwordx4 v[100:103], v[0:1], off offset:320
	global_load_dwordx4 v[96:99], v[0:1], off offset:352
	s_ashr_i32 s9, s8, 31
	s_lshl_b64 s[24:25], s[8:9], 11
	s_mul_i32 s9, s56, 0xc0
	v_or_b32_e32 v0, s9, v144
	v_mul_hi_u32 v2, v0, s34
	v_lshrrev_b32_e32 v150, 4, v2
	v_mad_u64_u32 v[0:1], s[10:11], v150, s35, v[0:1]
	s_lshl_b32 s6, s29, 8
	v_lshrrev_b32_e32 v1, 5, v2
	s_add_u32 s6, s4, s6
	v_bitop3_b32 v0, v0, v1, 7 bitop3:0x78
	s_addc_u32 s7, s5, 0
	v_lshl_add_u64 v[2:3], s[24:25], 0, v[150:151]
	v_cmp_lt_i32_e32 vcc, 15, v0
	v_lshlrev_b32_e32 v0, 3, v0
	s_and_saveexec_b64 s[10:11], vcc
	s_xor_b64 s[10:11], exec, s[10:11]
	v_lshlrev_b64 v[2:3], 7, v[2:3]
	v_lshl_add_u64 v[2:3], s[14:15], 0, v[2:3]
	v_add_u32_e32 v150, 0xffffff80, v0
	v_lshl_add_u64 v[160:161], v[150:151], 1, v[2:3]
	s_or_saveexec_b64 s[10:11], s[10:11]
	v_mov_b64_e32 v[162:163], 0x80
	s_xor_b64 exec, exec, s[10:11]
	v_lshlrev_b64 v[2:3], 11, v[2:3]
	v_lshl_add_u64 v[2:3], s[6:7], 0, v[2:3]
	v_ashrrev_i32_e32 v1, 31, v0
	v_lshl_add_u64 v[160:161], v[0:1], 1, v[2:3]
	v_mov_b64_e32 v[162:163], 0x800
	s_or_b64 exec, exec, s[10:11]
	s_mul_i32 s64, s56, 3
	s_add_i32 s57, s64, 1
	v_lshl_or_b32 v0, s57, 6, v144
	v_mul_hi_u32 v2, v0, s36
	v_lshrrev_b32_e32 v150, 2, v2
	v_mad_u64_u32 v[0:1], s[10:11], v150, s35, v[0:1]
	v_lshrrev_b32_e32 v1, 3, v2
	v_bitop3_b32 v0, v0, v1, 7 bitop3:0x78
	v_lshl_add_u64 v[2:3], s[24:25], 0, v[150:151]
	v_cmp_lt_i32_e32 vcc, 15, v0
	v_lshlrev_b32_e32 v0, 3, v0
	s_and_saveexec_b64 s[10:11], vcc
	s_xor_b64 s[10:11], exec, s[10:11]
	v_lshlrev_b64 v[2:3], 7, v[2:3]
	v_lshl_add_u64 v[2:3], s[14:15], 0, v[2:3]
	v_add_u32_e32 v150, 0xffffff80, v0
	v_lshl_add_u64 v[164:165], v[150:151], 1, v[2:3]
	s_or_saveexec_b64 s[10:11], s[10:11]
	v_mov_b64_e32 v[166:167], 0x80
	s_xor_b64 exec, exec, s[10:11]
	v_lshlrev_b64 v[2:3], 11, v[2:3]
	v_lshl_add_u64 v[2:3], s[6:7], 0, v[2:3]
	v_ashrrev_i32_e32 v1, 31, v0
	v_lshl_add_u64 v[164:165], v[0:1], 1, v[2:3]
	v_mov_b64_e32 v[166:167], 0x800
	s_or_b64 exec, exec, s[10:11]
	s_add_i32 s64, s64, 2
	v_lshl_or_b32 v0, s64, 6, v144
	v_mul_hi_u32 v2, v0, s36
	v_lshrrev_b32_e32 v150, 2, v2
	v_mad_u64_u32 v[0:1], s[10:11], v150, s35, v[0:1]
	v_lshrrev_b32_e32 v1, 3, v2
	v_bitop3_b32 v0, v0, v1, 7 bitop3:0x78
	v_lshl_add_u64 v[2:3], s[24:25], 0, v[150:151]
	v_cmp_lt_i32_e32 vcc, 15, v0
	v_lshlrev_b32_e32 v0, 3, v0
	s_and_saveexec_b64 s[10:11], vcc
	s_xor_b64 s[10:11], exec, s[10:11]
	v_lshlrev_b64 v[2:3], 7, v[2:3]
	v_lshl_add_u64 v[2:3], s[14:15], 0, v[2:3]
	v_add_u32_e32 v150, 0xffffff80, v0
	v_lshl_add_u64 v[168:169], v[150:151], 1, v[2:3]
	s_or_saveexec_b64 s[10:11], s[10:11]
	s_lshl_b32 s29, s29, 7
	v_mov_b64_e32 v[176:177], 0x80
	s_xor_b64 exec, exec, s[10:11]
	v_lshlrev_b64 v[2:3], 11, v[2:3]
	v_lshl_add_u64 v[2:3], s[6:7], 0, v[2:3]
	v_ashrrev_i32_e32 v1, 31, v0
	v_lshl_add_u64 v[168:169], v[0:1], 1, v[2:3]
	v_mov_b64_e32 v[176:177], 0x800
	s_or_b64 exec, exec, s[10:11]
	v_lshl_or_b32 v2, s56, 7, v144
	s_lshl_b32 s44, s8, 10
	s_or_b32 s54, s44, s29
	v_ashrrev_i32_e32 v0, 3, v2
	v_add_u32_e32 v0, s54, v0
	v_ashrrev_i32_e32 v1, 31, v0
	v_lshlrev_b64 v[64:65], 12, v[0:1]
	v_or_b32_e32 v0, 64, v2
	v_ashrrev_i32_e32 v1, 3, v0
	v_lshrrev_b32_e32 v77, 4, v0
	v_add_u32_e32 v0, s54, v1
	v_xor_b32_e32 v2, v77, v170
	v_ashrrev_i32_e32 v1, 31, v0
	v_lshlrev_b64 v[66:67], 12, v[0:1]
	v_lshlrev_b32_e32 v2, 4, v2
	v_lshl_add_u64 v[0:1], s[42:43], 0, v[66:67]
	v_and_b32_e32 v150, 0x70, v2
	s_sub_i32 s55, 0x4000, s13
	v_lshl_add_u64 v[180:181], v[0:1], 0, v[150:151]
	s_sub_i32 s10, 8, s8
	v_mad_u64_u32 v[0:1], s[8:9], v162, s55, v[160:161]
	s_mul_i32 s9, s56, 0xc00
	s_add_i32 s8, s9, 0
	s_lshl_b32 s13, s57, 10
	s_mov_b32 m0, s8
	s_add_i32 s50, s13, 0
	s_lshl_b32 s57, s64, 10
	s_mov_b32 s11, s17
	global_load_lds_dwordx4 v[0:1], off
	v_mad_u64_u32 v[0:1], s[66:67], v166, s55, v[164:165]
	s_mov_b32 m0, s50
	s_add_i32 s51, s57, 0
	s_lshl_b32 s64, s56, 11
	v_lshl_add_u64 v[178:179], v[152:153], 0, v[64:65]
	global_load_lds_dwordx4 v[0:1], off
	v_mad_u64_u32 v[0:1], s[66:67], v176, s55, v[168:169]
	s_mov_b32 m0, s51
	s_lshl_b64 s[10:11], s[10:11], 22
	s_add_i32 s56, s64, 0
	global_load_lds_dwordx4 v[0:1], off
	s_add_i32 m0, s56, 0x6000
	v_lshl_add_u64 v[0:1], v[178:179], 0, s[10:11]
	global_load_lds_dwordx4 v[0:1], off
	v_lshl_add_u64 v[0:1], v[180:181], 0, s[10:11]
	s_add_i32 m0, s56, 0x6400
	s_lshl_b32 s66, s52, 2
	global_load_lds_dwordx4 v[0:1], off
	s_add_i32 m0, s8, 0xa000
	s_waitcnt vmcnt(0) lgkmcnt(0)
	s_barrier
; __device__ __forceinline__ void attn_unit(LAS unsigned char* lds, const bf16_t* Q, const bf16_t* KN, const bf16_t* KPE, const bf16_t* VT, bf16_t* Y, float* ssq_b, int b, int h, int qg) {
;     ...
;         if (j + 1 < ntiles) AT_DMA(j + 1);
;         if (j <= cw) {
;             const LAS unsigned char* kb = lds + (j & 1) * KV_BYTES; const LAS unsigned char* vb = kb + KS_BYTES;
;             f32x16 s0, s1;
; #pragma unroll
;             for (int i = 0; i < 16; ++i) { s0[i] = 0.f; s1[i] = 0.f; }
;             __builtin_amdgcn_s_setprio(1);
;             {
;                 bf16x8 a0n = *(const LAS bf16x8*)(kb + kbase0), a1n = *(const LAS bf16x8*)(kb + (kbase0 + 32u * 384u));
; #pragma unroll
;                 for (int ks = 0; ks < 12; ++ks) {
;                     const bf16x8 a0 = a0n, a1 = a1n;
;                     if (ks + 1 < 12) { const unsigned off = (kbase0 ^ (unsigned)(((2 * (ks + 1)) & 7) << 4)) + (unsigned)(((2 * (ks + 1)) & 24) << 4);
;                         a0n = *(const LAS bf16x8*)(kb + off); a1n = *(const LAS bf16x8*)(kb + (off + 32u * 384u)); }
;                     s0 = __builtin_amdgcn_mfma_f32_32x32x16_bf16(a0, qf[ks], s0, 0, 0, 0);
;                     s1 = __builtin_amdgcn_mfma_f32_32x32x16_bf16(a1, qf[ks], s1, 0, 0, 0);
;                 }
;             }
;             __builtin_amdgcn_s_setprio(0);
;             if (j == 0) {
; #pragma unroll
;                 for (int i = 0; i < 16; ++i) { if (i >= 8) s0[i] = -INFINITY; s1[i] = -INFINITY; }
;             }
;             float mx = s0[0];
; #pragma unroll
;             for (int i = 1; i < 16; ++i) mx = fmaxf(mx, s0[i]);
; #pragma unroll
;             for (int i = 0; i < 16; ++i) mx = fmaxf(mx, s1[i]);
;             mx = fmaxf(mx, __shfl_xor(mx, 32));
;             const bool upd = __builtin_amdgcn_ballot_w64(mx - mrun > 8.0f) != 0ull;
;             const float mn = upd ? fmaxf(mrun, mx) : mrun; const float alpha = upd ? fexp2(mrun - mn) : 1.0f; mrun = mn;
;             s0 = s0 - mn; s1 = s1 - mn;
; #pragma unroll
;             for (int i = 0; i < 16; ++i) { s0[i] = fexp2(s0[i]); s1[i] = fexp2(s1[i]); }
;             const f32x16 t16 = s0 + s1;
;             typedef float f32x8_ __attribute__((ext_vector_type(8)));
;             const f32x8_ t8 = __builtin_shufflevector(t16, t16, 0, 1, 2, 3, 4, 5, 6, 7) + __builtin_shufflevector(t16, t16, 8, 9, 10, 11, 12, 13, 14, 15);
	global_load_lds_dwordx4 v[160:161], off
	s_add_i32 m0, s50, 0xa000
	s_lshr_b32 s8, s53, 7
	global_load_lds_dwordx4 v[164:165], off
	s_add_i32 m0, s51, 0xa000
	s_add_i32 s65, s8, s66
	global_load_lds_dwordx4 v[168:169], off
	s_add_i32 m0, s56, 0x10000
	s_add_i32 s65, s65, 1
	global_load_lds_dwordx4 v[178:179], off
	s_add_i32 m0, s56, 0x10400
	s_lshr_b32 s56, s39, 3
	global_load_lds_dwordx4 v[180:181], off
	s_setprio 1
	v_add_u32_e32 v209, 0, v197
	v_add_u32_e32 v210, 0, v199
	v_add_u32_e32 v208, 0, v200
	v_add_u32_e32 v207, 0, v201
	ds_read_b128 v[0:3], v209
	ds_read_b128 v[16:19], v210
	ds_read_b128 v[20:23], v208
	ds_read_b128 v[24:27], v207
	ds_read_b128 v[28:31], v209 offset:128
	ds_read_b128 v[32:35], v210 offset:128
	ds_read_b128 v[36:39], v208 offset:128
	ds_read_b128 v[40:43], v207 offset:128
	ds_read_b128 v[44:47], v209 offset:256
	ds_read_b128 v[48:51], v210 offset:256
	ds_read_b128 v[52:55], v208 offset:256
	ds_read_b128 v[56:59], v207 offset:256
	s_waitcnt lgkmcnt(11)
	v_mfma_f32_32x32x16_bf16 v[0:15], v[0:3], v[140:143], 0
	s_waitcnt lgkmcnt(10)
	v_mfma_f32_32x32x16_bf16 v[0:15], v[16:19], v[136:139], v[0:15]
	s_waitcnt lgkmcnt(9)
	v_mfma_f32_32x32x16_bf16 v[0:15], v[20:23], v[132:135], v[0:15]
	s_waitcnt lgkmcnt(8)
	v_mfma_f32_32x32x16_bf16 v[0:15], v[24:27], v[128:131], v[0:15]
	s_waitcnt lgkmcnt(7)
	v_mfma_f32_32x32x16_bf16 v[0:15], v[28:31], v[124:127], v[0:15]
	s_waitcnt lgkmcnt(6)
	v_mfma_f32_32x32x16_bf16 v[0:15], v[32:35], v[120:123], v[0:15]
	s_waitcnt lgkmcnt(5)
	v_mfma_f32_32x32x16_bf16 v[0:15], v[36:39], v[116:119], v[0:15]
	s_waitcnt lgkmcnt(4)
	v_mfma_f32_32x32x16_bf16 v[0:15], v[40:43], v[112:115], v[0:15]
	s_waitcnt lgkmcnt(3)
	v_mfma_f32_32x32x16_bf16 v[0:15], v[44:47], v[108:111], v[0:15]
	s_waitcnt lgkmcnt(2)
	v_mfma_f32_32x32x16_bf16 v[0:15], v[48:51], v[104:107], v[0:15]
	s_waitcnt lgkmcnt(1)
	v_mfma_f32_32x32x16_bf16 v[0:15], v[52:55], v[100:103], v[0:15]
	s_waitcnt lgkmcnt(0)
	v_mfma_f32_32x32x16_bf16 v[0:15], v[56:59], v[96:99], v[0:15]
	s_setprio 0
	s_nop 10
	v_max3_f32 v8, v0, v1, v2
	v_max3_f32 v8, v8, v3, v4
	v_max3_f32 v8, v8, v5, v6
	v_max3_f32 v8, v8, v7, s37
	ds_bpermute_b32 v9, v205, v8
	s_waitcnt lgkmcnt(0)
	v_max_f32_e32 v9, v9, v9
	v_max_f32_e32 v8, v8, v9
	v_add_f32_e32 v9, 0x7f800000, v8
	v_cmp_lt_f32_e32 vcc, s38, v9
	s_cmp_eq_u64 vcc, 0
	v_max_f32_e32 v8, 0xff800000, v8
	s_cselect_b64 vcc, -1, 0
	v_cndmask_b32_e32 v163, v8, v206, vcc
	v_sub_f32_e32 v8, 0xff800000, v163
	v_sub_f32_e32 v7, v7, v163
	v_sub_f32_e32 v6, v6, v163
	v_sub_f32_e32 v5, v5, v163
	v_sub_f32_e32 v4, v4, v163
	v_sub_f32_e32 v3, v3, v163
	v_sub_f32_e32 v2, v2, v163
	v_sub_f32_e32 v1, v1, v163
	v_sub_f32_e32 v0, v0, v163
	v_exp_f32_e32 v76, v8
	v_exp_f32_e32 v16, v0
	v_exp_f32_e32 v17, v1
	v_exp_f32_e32 v18, v2
	v_exp_f32_e32 v19, v3
	v_exp_f32_e32 v20, v6
	v_exp_f32_e32 v21, v7
	v_exp_f32_e32 v22, v4
	v_exp_f32_e32 v23, v5
	v_pk_add_f32 v[0:1], v[76:77], v[18:19] op_sel_hi:[0,1]
	v_pk_add_f32 v[2:3], v[76:77], v[20:21] op_sel_hi:[0,1]
	v_pk_add_f32 v[4:5], v[76:77], v[16:17] op_sel_hi:[0,1]
	v_pk_add_f32 v[6:7], v[76:77], v[22:23] op_sel_hi:[0,1]
	v_pk_fma_f32 v[6:7], v[76:77], 2.0, v[6:7] op_sel_hi:[0,0,1]
	v_pk_fma_f32 v[4:5], v[76:77], 2.0, v[4:5] op_sel_hi:[0,0,1]
	v_pk_fma_f32 v[2:3], v[76:77], 2.0, v[2:3] op_sel_hi:[0,0,1]
	v_pk_fma_f32 v[0:1], v[76:77], 2.0, v[0:1] op_sel_hi:[0,0,1]
	v_pk_add_f32 v[0:1], v[0:1], v[2:3]
	v_pk_add_f32 v[2:3], v[4:5], v[6:7]
	v_cvt_pk_bf16_f32 v68, v16, v17
	v_cvt_pk_bf16_f32 v69, v18, v19
	v_cvt_pk_bf16_f32 v70, v22, v23
	v_cvt_pk_bf16_f32 v71, v20, v21
	s_nop 0
	v_pk_mov_b32 v[4:5], v[2:3], v[0:1] op_sel:[1,0]
	v_mov_b32_e32 v3, v1
	v_pk_add_f32 v[0:1], v[4:5], v[2:3]
	s_nop 0
	v_add_f32_e32 v1, v0, v1
	v_mul_f32_e32 v0, 0, v76
	v_cndmask_b32_e64 v0, v0, 0, vcc
	v_add_f32_e32 v157, v0, v1
	v_mov_b32_e32 v1, v0
	v_mov_b32_e32 v2, v0
	v_mov_b32_e32 v3, v0
	v_mov_b32_e32 v4, v0
	v_mov_b32_e32 v5, v0
	v_mov_b32_e32 v6, v0
	v_mov_b32_e32 v7, v0
	v_mov_b32_e32 v8, v0
	v_mov_b32_e32 v9, v0
	v_mov_b32_e32 v10, v0
	v_mov_b32_e32 v11, v0
	v_mov_b32_e32 v12, v0
	v_mov_b32_e32 v13, v0
	v_mov_b32_e32 v14, v0
	v_mov_b32_e32 v15, v0
	s_setprio 1
	v_add_u32_e32 v215, 0, v198
	ds_read_b128 v[16:19], v215 offset:24576
	ds_read_b128 v[72:75], v215 offset:32768
	s_waitcnt lgkmcnt(0)
	v_mfma_f32_32x32x16_bf16 v[48:63], v[16:19], v[68:71], v[0:15]
	ds_read_b128 v[16:19], v215 offset:28672
	s_waitcnt lgkmcnt(0)
	v_mfma_f32_32x32x16_bf16 v[32:47], v[16:19], v[68:71], v[0:15]
	v_mfma_f32_32x32x16_bf16 v[16:31], v[72:75], v[68:71], v[0:15]
	ds_read_b128 v[72:75], v215 offset:36864
	s_waitcnt lgkmcnt(0)
	v_mfma_f32_32x32x16_bf16 v[0:15], v[72:75], v[68:71], v[0:15]
	s_setprio 0
	v_add_u32_e32 v213, 0, v202
	v_add_u32_e32 v214, 0, v203
	v_add_u32_e32 v216, 0, v204
	v_lshl_add_u64 v[182:183], v[154:155], 0, v[64:65]
	v_bitop3_b32 v64, v77, 7, v170 bitop3:0x48
	v_lshl_or_b32 v66, v64, 4, v66
	v_lshlrev_b32_e32 v150, 6, v176
	v_lshlrev_b32_e32 v188, 6, v166
	v_mov_b32_e32 v189, v151
	v_lshlrev_b32_e32 v192, 6, v162
	v_mov_b32_e32 v193, v151
	v_lshl_add_u64 v[184:185], s[18:19], 0, v[66:67]
	v_lshl_add_u64 v[186:187], v[168:169], 0, v[150:151]
	v_lshl_add_u64 v[190:191], v[164:165], 0, v[188:189]
	v_lshl_add_u64 v[194:195], v[160:161], 0, v[192:193]
	s_mov_b32 s67, -3
	s_waitcnt vmcnt(0)
	s_barrier

; #define LAS __attribute__((address_space(3)))
; __device__ __forceinline__ int pi32(int r) { return (r & 0x13) | ((r & 4) << 1) | ((r & 8) >> 1); }
; __device__ __forceinline__ void attn_unit(LAS unsigned char* lds, const bf16_t* Q, const bf16_t* KN, const bf16_t* KPE, const bf16_t* VT, bf16_t* Y, float* ssq_b, int b, int h, int qg) {
;     const int tid = threadIdx.x, wid = __builtin_amdgcn_readfirstlane(tid >> 6), lane = tid & 63, q = lane & 31, hh = lane >> 5;
;     const int t0 = 16 + 256 * qg, c0 = 1 + 4 * qg, cw = c0 + (wid >> 1), ntiles = c0 + 4;
;     bf16x8 qf[12];
;     {
;         const bf16_t* qp = Q + (size_t)(b * 2048 + (t0 - 16) + 32 * wid + q) * 1536 + h * 192 + 8 * hh;
; #pragma unroll
;         for (int ks = 0; ks < 12; ++ks) qf[ks] = *(const bf16x8*)(qp + 16 * ks);
;     }
;     f32x16 o[4];
; #pragma unroll
;     for (int d = 0; d < 4; ++d)
; #pragma unroll
;         for (int i = 0; i < 16; ++i) o[d][i] = 0.f;
;     float mrun = -INFINITY, lsum = 0.f;
;     const char* ksrc[3]; unsigned kstr[3]; const char* vsrc[2];
; #pragma unroll
;     for (int i = 0; i < 3; ++i) {
;         const int s = 64 * (wid * 3 + i) + lane; const int key = s / 24, pos = s - key * 24; const int pc = pos ^ ((key >> 1) & 7);
;         const size_t row = (size_t)b * 2048 + key;
;         if (pc < 16) { ksrc[i] = (const char*)(KN + row * 1024 + h * 128 + pc * 8); kstr[i] = 2048u; }
;         else { ksrc[i] = (const char*)(KPE + row * 64 + (pc - 16) * 8); kstr[i] = 128u; }
;     }
; #pragma unroll
;     for (int i = 0; i < 2; ++i) {
;         const int s = 64 * (wid * 2 + i) + lane; const int d = s >> 3, pos = s & 7; const int pc = pos ^ ((d >> 1) & 7);
;         vsrc[i] = (const char*)(VT + ((size_t)((b * 8 + h) * 128 + d)) * 2048 + pc * 8);
;     }
;     ...
;     const int key0 = pi32(q);
;     const unsigned kbase0 = (unsigned)(key0 * 384) + (unsigned)(((hh ^ ((key0 >> 1) & 7))) << 4);
;     const unsigned vbase0 = (unsigned)(q * 128) + (unsigned)((hh ^ ((q >> 1) & 7)) << 4);
;     AT_DMA(0); __syncthreads();
.LBB0_680:
	s_or_b64 exec, exec, s[8:9]
	v_readfirstlane_b32 s52, v170
	s_lshr_b32 s53, s52, 6
	s_lshl_b32 s13, s45, 8
	s_lshl_b32 s28, s53, 5
	v_or_b32_e32 v0, s13, v211
	v_add_u32_e32 v2, s28, v0
	s_waitcnt lgkmcnt(0)
	v_mov_b64_e32 v[0:1], s[60:61]
	v_mad_i64_i32 v[0:1], s[8:9], v2, s31, v[0:1]
	v_lshl_add_u64 v[0:1], v[0:1], 0, s[16:17]
	v_mov_b32_e32 v157, v151
	v_lshl_add_u64 v[0:1], v[0:1], 0, v[156:157]
	global_load_dwordx4 v[140:143], v[0:1], off
	global_load_dwordx4 v[136:139], v[0:1], off offset:32
	global_load_dwordx4 v[132:135], v[0:1], off offset:64
	global_load_dwordx4 v[128:131], v[0:1], off offset:96
	global_load_dwordx4 v[124:127], v[0:1], off offset:128
	global_load_dwordx4 v[120:123], v[0:1], off offset:160
	global_load_dwordx4 v[116:119], v[0:1], off offset:192
	global_load_dwordx4 v[112:115], v[0:1], off offset:224
	global_load_dwordx4 v[108:111], v[0:1], off offset:256
	global_load_dwordx4 v[104:107], v[0:1], off offset:288
	global_load_dwordx4 v[100:103], v[0:1], off offset:320
	global_load_dwordx4 v[96:99], v[0:1], off offset:352
	s_mul_i32 s8, s53, 0xc0
	v_or_b32_e32 v0, s8, v144
	v_mul_hi_u32 v2, v0, s34
	v_lshrrev_b32_e32 v150, 4, v2
	v_mad_u64_u32 v[0:1], s[8:9], v150, s35, v[0:1]
	v_lshrrev_b32_e32 v1, 5, v2
	v_bitop3_b32 v0, v0, v1, 7 bitop3:0x78
	v_lshl_add_u64 v[2:3], s[24:25], 0, v[150:151]
	v_cmp_lt_i32_e32 vcc, 15, v0
	v_lshlrev_b32_e32 v0, 3, v0
	s_and_saveexec_b64 s[8:9], vcc
	s_xor_b64 s[8:9], exec, s[8:9]
	v_lshlrev_b64 v[2:3], 7, v[2:3]
	v_lshl_add_u64 v[2:3], s[14:15], 0, v[2:3]
	v_add_u32_e32 v150, 0xffffff80, v0
	v_lshl_add_u64 v[160:161], v[150:151], 1, v[2:3]
	s_or_saveexec_b64 s[8:9], s[8:9]
	v_mov_b64_e32 v[162:163], 0x80
	s_xor_b64 exec, exec, s[8:9]
	v_lshlrev_b64 v[2:3], 11, v[2:3]
	v_lshl_add_u64 v[2:3], s[6:7], 0, v[2:3]
	v_ashrrev_i32_e32 v1, 31, v0
	v_lshl_add_u64 v[160:161], v[0:1], 1, v[2:3]
	v_mov_b64_e32 v[162:163], 0x800
	s_or_b64 exec, exec, s[8:9]
	s_mul_i32 s57, s53, 3
	s_add_i32 s16, s57, 1
	v_lshl_or_b32 v0, s16, 6, v144
	v_mul_hi_u32 v2, v0, s36
	v_lshrrev_b32_e32 v150, 2, v2
	v_mad_u64_u32 v[0:1], s[8:9], v150, s35, v[0:1]
	v_lshrrev_b32_e32 v1, 3, v2
	v_bitop3_b32 v0, v0, v1, 7 bitop3:0x78
	v_lshl_add_u64 v[2:3], s[24:25], 0, v[150:151]
	v_cmp_lt_i32_e32 vcc, 15, v0
	v_lshlrev_b32_e32 v0, 3, v0
	s_and_saveexec_b64 s[8:9], vcc
	s_xor_b64 s[8:9], exec, s[8:9]
	v_lshlrev_b64 v[2:3], 7, v[2:3]
	v_lshl_add_u64 v[2:3], s[14:15], 0, v[2:3]
	v_add_u32_e32 v150, 0xffffff80, v0
	v_lshl_add_u64 v[164:165], v[150:151], 1, v[2:3]
	s_or_saveexec_b64 s[8:9], s[8:9]
	v_mov_b64_e32 v[166:167], 0x80
	s_xor_b64 exec, exec, s[8:9]
	v_lshlrev_b64 v[2:3], 11, v[2:3]
	v_lshl_add_u64 v[2:3], s[6:7], 0, v[2:3]
	v_ashrrev_i32_e32 v1, 31, v0
	v_lshl_add_u64 v[164:165], v[0:1], 1, v[2:3]
	v_mov_b64_e32 v[166:167], 0x800
	s_or_b64 exec, exec, s[8:9]
	s_add_i32 s57, s57, 2
	v_lshl_or_b32 v0, s57, 6, v144
	v_mul_hi_u32 v2, v0, s36
	v_lshrrev_b32_e32 v150, 2, v2
	v_mad_u64_u32 v[0:1], s[8:9], v150, s35, v[0:1]
	v_lshrrev_b32_e32 v1, 3, v2
	v_bitop3_b32 v0, v0, v1, 7 bitop3:0x78
	v_lshl_add_u64 v[2:3], s[24:25], 0, v[150:151]
	v_cmp_lt_i32_e32 vcc, 15, v0
	v_lshlrev_b32_e32 v0, 3, v0
	s_and_saveexec_b64 s[8:9], vcc
	s_xor_b64 s[8:9], exec, s[8:9]
	v_lshlrev_b64 v[2:3], 7, v[2:3]
	v_lshl_add_u64 v[2:3], s[14:15], 0, v[2:3]
	v_add_u32_e32 v150, 0xffffff80, v0
	v_lshl_add_u64 v[168:169], v[150:151], 1, v[2:3]
	s_or_saveexec_b64 s[8:9], s[8:9]
	v_mov_b64_e32 v[176:177], 0x80
	s_xor_b64 exec, exec, s[8:9]
	v_lshlrev_b64 v[2:3], 11, v[2:3]
	v_lshl_add_u64 v[2:3], s[6:7], 0, v[2:3]
	v_ashrrev_i32_e32 v1, 31, v0
	v_lshl_add_u64 v[168:169], v[0:1], 1, v[2:3]
	v_mov_b64_e32 v[176:177], 0x800
	s_or_b64 exec, exec, s[8:9]
	v_lshl_or_b32 v2, s53, 7, v144
	v_ashrrev_i32_e32 v73, 3, v2
	v_add_u32_e32 v0, s54, v73
	v_ashrrev_i32_e32 v1, 31, v0
	v_lshlrev_b64 v[0:1], 12, v[0:1]
	v_lshl_add_u64 v[178:179], v[152:153], 0, v[0:1]
	v_or_b32_e32 v0, 64, v2
	v_ashrrev_i32_e32 v74, 3, v0
	v_lshrrev_b32_e32 v75, 4, v0
	v_add_u32_e32 v0, s54, v74
	v_xor_b32_e32 v2, v75, v170
	v_ashrrev_i32_e32 v1, 31, v0
	v_lshlrev_b64 v[0:1], 12, v[0:1]
	v_lshlrev_b32_e32 v2, 4, v2
	v_lshl_add_u64 v[0:1], s[42:43], 0, v[0:1]
	v_and_b32_e32 v150, 0x70, v2
	v_lshl_add_u64 v[180:181], v[0:1], 0, v[150:151]
	v_mad_u64_u32 v[0:1], s[6:7], v162, s55, v[160:161]
	s_mul_i32 s7, s53, 0xc00
	s_add_i32 s6, s7, 0
	s_mov_b32 m0, s6
	s_nop 0
	global_load_lds_dwordx4 v[0:1], off
	v_mad_u64_u32 v[0:1], s[8:9], v166, s55, v[164:165]
	s_lshl_b32 s8, s16, 10
	s_add_i32 s16, s8, 0
	s_mov_b32 m0, s16
	s_lshl_b32 s9, s57, 10
	global_load_lds_dwordx4 v[0:1], off
	v_mad_u64_u32 v[0:1], s[54:55], v176, s55, v[168:169]
	s_add_i32 s50, s9, 0
	s_lshl_b32 s54, s53, 11
	s_mov_b32 m0, s50
	s_add_i32 s51, s54, 0
	global_load_lds_dwordx4 v[0:1], off
	s_add_i32 m0, s51, 0x6000
	v_lshl_add_u64 v[0:1], v[178:179], 0, s[10:11]
	global_load_lds_dwordx4 v[0:1], off
	v_lshl_add_u64 v[0:1], v[180:181], 0, s[10:11]
	s_add_i32 m0, s51, 0x6400
	s_lshl_b32 s11, s45, 2
	global_load_lds_dwordx4 v[0:1], off
	s_add_i32 m0, s6, 0xa000
	s_waitcnt vmcnt(0) lgkmcnt(0)
	s_barrier
; __device__ __forceinline__ void attn_unit(LAS unsigned char* lds, const bf16_t* Q, const bf16_t* KN, const bf16_t* KPE, const bf16_t* VT, bf16_t* Y, float* ssq_b, int b, int h, int qg) {
;     ...
;         if (j + 1 < ntiles) AT_DMA(j + 1);
;         if (j <= cw) {
;             const LAS unsigned char* kb = lds + (j & 1) * KV_BYTES; const LAS unsigned char* vb = kb + KS_BYTES;
;             f32x16 s0, s1;
; #pragma unroll
;             for (int i = 0; i < 16; ++i) { s0[i] = 0.f; s1[i] = 0.f; }
;             __builtin_amdgcn_s_setprio(1);
;             {
;                 bf16x8 a0n = *(const LAS bf16x8*)(kb + kbase0), a1n = *(const LAS bf16x8*)(kb + (kbase0 + 32u * 384u));
; #pragma unroll
;                 for (int ks = 0; ks < 12; ++ks) {
;                     const bf16x8 a0 = a0n, a1 = a1n;
;                     if (ks + 1 < 12) { const unsigned off = (kbase0 ^ (unsigned)(((2 * (ks + 1)) & 7) << 4)) + (unsigned)(((2 * (ks + 1)) & 24) << 4);
;                         a0n = *(const LAS bf16x8*)(kb + off); a1n = *(const LAS bf16x8*)(kb + (off + 32u * 384u)); }
;                     s0 = __builtin_amdgcn_mfma_f32_32x32x16_bf16(a0, qf[ks], s0, 0, 0, 0);
;                     s1 = __builtin_amdgcn_mfma_f32_32x32x16_bf16(a1, qf[ks], s1, 0, 0, 0);
;                 }
;             }
;             __builtin_amdgcn_s_setprio(0);
;             if (j == 0) {
; #pragma unroll
;                 for (int i = 0; i < 16; ++i) { if (i >= 8) s0[i] = -INFINITY; s1[i] = -INFINITY; }
;             }
;             float mx = s0[0];
; #pragma unroll
;             for (int i = 1; i < 16; ++i) mx = fmaxf(mx, s0[i]);
; #pragma unroll
;             for (int i = 0; i < 16; ++i) mx = fmaxf(mx, s1[i]);
;             mx = fmaxf(mx, __shfl_xor(mx, 32));
;             const bool upd = __builtin_amdgcn_ballot_w64(mx - mrun > 8.0f) != 0ull;
;             const float mn = upd ? fmaxf(mrun, mx) : mrun; const float alpha = upd ? fexp2(mrun - mn) : 1.0f; mrun = mn;
;             s0 = s0 - mn; s1 = s1 - mn;
; #pragma unroll
;             for (int i = 0; i < 16; ++i) { s0[i] = fexp2(s0[i]); s1[i] = fexp2(s1[i]); }
;             const f32x16 t16 = s0 + s1;
;             typedef float f32x8_ __attribute__((ext_vector_type(8)));
;             const f32x8_ t8 = __builtin_shufflevector(t16, t16, 0, 1, 2, 3, 4, 5, 6, 7) + __builtin_shufflevector(t16, t16, 8, 9, 10, 11, 12, 13, 14, 15);
	global_load_lds_dwordx4 v[160:161], off
	s_add_i32 m0, s16, 0xa000
	s_lshr_b32 s6, s52, 7
	global_load_lds_dwordx4 v[164:165], off
	s_add_i32 m0, s50, 0xa000
	s_add_i32 s10, s6, s11
	global_load_lds_dwordx4 v[168:169], off
	s_add_i32 m0, s51, 0x10000
	s_and_b32 s6, s56, 3
	global_load_lds_dwordx4 v[178:179], off
	s_add_i32 m0, s51, 0x10400
	s_add_i32 s10, s10, 1
	global_load_lds_dwordx4 v[180:181], off
	s_lshl_b32 s16, s6, 2
	s_setprio 1
	ds_read_b128 v[0:3], v209
	ds_read_b128 v[16:19], v210
	ds_read_b128 v[20:23], v208
	ds_read_b128 v[24:27], v207
	ds_read_b128 v[28:31], v209 offset:128
	ds_read_b128 v[32:35], v210 offset:128
	ds_read_b128 v[36:39], v208 offset:128
	ds_read_b128 v[40:43], v207 offset:128
	ds_read_b128 v[44:47], v209 offset:256
	ds_read_b128 v[48:51], v210 offset:256
	ds_read_b128 v[52:55], v208 offset:256
	ds_read_b128 v[56:59], v207 offset:256
	s_waitcnt lgkmcnt(11)
	v_mfma_f32_32x32x16_bf16 v[0:15], v[0:3], v[140:143], 0
	s_waitcnt lgkmcnt(10)
	v_mfma_f32_32x32x16_bf16 v[0:15], v[16:19], v[136:139], v[0:15]
	s_waitcnt lgkmcnt(9)
	v_mfma_f32_32x32x16_bf16 v[0:15], v[20:23], v[132:135], v[0:15]
	s_waitcnt lgkmcnt(8)
	v_mfma_f32_32x32x16_bf16 v[0:15], v[24:27], v[128:131], v[0:15]
	s_waitcnt lgkmcnt(7)
	v_mfma_f32_32x32x16_bf16 v[0:15], v[28:31], v[124:127], v[0:15]
	s_waitcnt lgkmcnt(6)
	v_mfma_f32_32x32x16_bf16 v[0:15], v[32:35], v[120:123], v[0:15]
	s_waitcnt lgkmcnt(5)
	v_mfma_f32_32x32x16_bf16 v[0:15], v[36:39], v[116:119], v[0:15]
	s_waitcnt lgkmcnt(4)
	v_mfma_f32_32x32x16_bf16 v[0:15], v[40:43], v[112:115], v[0:15]
	s_waitcnt lgkmcnt(3)
	v_mfma_f32_32x32x16_bf16 v[0:15], v[44:47], v[108:111], v[0:15]
	s_waitcnt lgkmcnt(2)
	v_mfma_f32_32x32x16_bf16 v[0:15], v[48:51], v[104:107], v[0:15]
	s_waitcnt lgkmcnt(1)
	v_mfma_f32_32x32x16_bf16 v[0:15], v[52:55], v[100:103], v[0:15]
	s_waitcnt lgkmcnt(0)
	v_mfma_f32_32x32x16_bf16 v[0:15], v[56:59], v[96:99], v[0:15]
	s_setprio 0
	s_nop 10
	v_max3_f32 v8, v0, v1, v2
	v_max3_f32 v8, v8, v3, v4
	v_max3_f32 v8, v8, v5, v6
	v_max3_f32 v8, v8, v7, s37
	ds_bpermute_b32 v9, v205, v8
	s_waitcnt lgkmcnt(0)
	v_max_f32_e32 v9, v9, v9
	v_max_f32_e32 v8, v8, v9
	v_add_f32_e32 v9, 0x7f800000, v8
	v_cmp_lt_f32_e32 vcc, s38, v9
	s_cmp_eq_u64 vcc, 0
	v_max_f32_e32 v8, 0xff800000, v8
	s_cselect_b64 vcc, -1, 0
	v_cndmask_b32_e32 v163, v8, v206, vcc
	v_sub_f32_e32 v8, 0xff800000, v163
	v_sub_f32_e32 v7, v7, v163
	v_sub_f32_e32 v6, v6, v163
	v_sub_f32_e32 v5, v5, v163
	v_sub_f32_e32 v4, v4, v163
	v_sub_f32_e32 v3, v3, v163
	v_sub_f32_e32 v2, v2, v163
	v_sub_f32_e32 v1, v1, v163
	v_sub_f32_e32 v0, v0, v163
	v_exp_f32_e32 v72, v8
	v_exp_f32_e32 v16, v0
	v_exp_f32_e32 v17, v1
	v_exp_f32_e32 v18, v2
	v_exp_f32_e32 v19, v3
	v_exp_f32_e32 v20, v6
	v_exp_f32_e32 v21, v7
	v_exp_f32_e32 v22, v4
	v_exp_f32_e32 v23, v5
	v_pk_add_f32 v[0:1], v[72:73], v[18:19] op_sel_hi:[0,1]
	v_pk_add_f32 v[2:3], v[72:73], v[20:21] op_sel_hi:[0,1]
	v_pk_add_f32 v[4:5], v[72:73], v[16:17] op_sel_hi:[0,1]
	v_pk_add_f32 v[6:7], v[72:73], v[22:23] op_sel_hi:[0,1]
	v_pk_fma_f32 v[6:7], v[72:73], 2.0, v[6:7] op_sel_hi:[0,0,1]
	v_pk_fma_f32 v[4:5], v[72:73], 2.0, v[4:5] op_sel_hi:[0,0,1]
	v_pk_fma_f32 v[2:3], v[72:73], 2.0, v[2:3] op_sel_hi:[0,0,1]
	v_pk_fma_f32 v[0:1], v[72:73], 2.0, v[0:1] op_sel_hi:[0,0,1]
	v_pk_add_f32 v[0:1], v[0:1], v[2:3]
	v_pk_add_f32 v[2:3], v[4:5], v[6:7]
	v_cvt_pk_bf16_f32 v64, v16, v17
	v_cvt_pk_bf16_f32 v65, v18, v19
	v_cvt_pk_bf16_f32 v66, v22, v23
	v_cvt_pk_bf16_f32 v67, v20, v21
	s_nop 0
	v_pk_mov_b32 v[4:5], v[2:3], v[0:1] op_sel:[1,0]
	v_mov_b32_e32 v3, v1
	v_pk_add_f32 v[0:1], v[4:5], v[2:3]
	s_nop 0
	v_add_f32_e32 v1, v0, v1
	v_mul_f32_e32 v0, 0, v72
	v_cndmask_b32_e64 v0, v0, 0, vcc
	v_add_f32_e32 v157, v0, v1
	v_mov_b32_e32 v1, v0
	v_mov_b32_e32 v2, v0
	v_mov_b32_e32 v3, v0
	v_mov_b32_e32 v4, v0
	v_mov_b32_e32 v5, v0
	v_mov_b32_e32 v6, v0
	v_mov_b32_e32 v7, v0
	v_mov_b32_e32 v8, v0
	v_mov_b32_e32 v9, v0
	v_mov_b32_e32 v10, v0
	v_mov_b32_e32 v11, v0
	v_mov_b32_e32 v12, v0
	v_mov_b32_e32 v13, v0
	v_mov_b32_e32 v14, v0
	v_mov_b32_e32 v15, v0
	s_setprio 1
	ds_read_b128 v[16:19], v215 offset:24576
	ds_read_b128 v[68:71], v215 offset:32768
	s_waitcnt lgkmcnt(0)
	v_mfma_f32_32x32x16_bf16 v[48:63], v[16:19], v[64:67], v[0:15]
	ds_read_b128 v[16:19], v215 offset:28672
	s_waitcnt lgkmcnt(0)
	v_mfma_f32_32x32x16_bf16 v[32:47], v[16:19], v[64:67], v[0:15]
	v_mfma_f32_32x32x16_bf16 v[16:31], v[68:71], v[64:67], v[0:15]
	ds_read_b128 v[68:71], v215 offset:36864
	s_waitcnt lgkmcnt(0)
	v_mfma_f32_32x32x16_bf16 v[0:15], v[68:71], v[64:67], v[0:15]
	s_setprio 0
	s_add_i32 s29, s29, s44
	v_add_u32_e32 v64, s29, v73
	v_ashrrev_i32_e32 v65, 31, v64
	v_lshlrev_b64 v[64:65], 12, v[64:65]
	v_lshl_add_u64 v[182:183], v[154:155], 0, v[64:65]
	v_add_u32_e32 v64, s29, v74
	v_ashrrev_i32_e32 v65, 31, v64
	v_lshlrev_b64 v[64:65], 12, v[64:65]
	v_bitop3_b32 v66, v75, 7, v170 bitop3:0x48
	v_lshl_or_b32 v64, v66, 4, v64
	v_lshlrev_b32_e32 v150, 6, v176
	v_lshlrev_b32_e32 v188, 6, v166
	v_mov_b32_e32 v189, v151
	v_lshlrev_b32_e32 v192, 6, v162
	v_mov_b32_e32 v193, v151
	v_lshl_add_u64 v[184:185], s[18:19], 0, v[64:65]
	v_lshl_add_u64 v[186:187], v[168:169], 0, v[150:151]
	v_lshl_add_u64 v[190:191], v[164:165], 0, v[188:189]
	v_lshl_add_u64 v[194:195], v[160:161], 0, v[192:193]
	s_mov_b32 s29, -3
	s_waitcnt vmcnt(0)
	s_barrier
